# v25: v17 without wave-half sleep, attention softmax exp/cvt chunks software-pipelined under P@V MFMAs (k-step-major PV order, in-place P frags, V frags in v194-209)
# baseline (speedup 1.0000x reference)
.LBB0_571:
	v_cndmask_b32_e64 v249, v220, v249, s[6:7]
	v_mul_f32_e32 v252, 0xbe0293ee, v249
	ds_read_b64_tr_b16 v[194:195], v224 offset:0
	ds_read_b64_tr_b16 v[196:197], v224 offset:0x800
	ds_read_b64_tr_b16 v[198:199], v224 offset:0x200
	ds_read_b64_tr_b16 v[200:201], v224 offset:0xa00
	ds_read_b64_tr_b16 v[202:203], v224 offset:0x400
	ds_read_b64_tr_b16 v[204:205], v224 offset:0xc00
	v_fmamk_f32 v146, v146, 0x3e0293ee, v252
	v_fmamk_f32 v147, v147, 0x3e0293ee, v252
	v_fmamk_f32 v148, v148, 0x3e0293ee, v252
	v_fmamk_f32 v149, v149, 0x3e0293ee, v252
	v_fmamk_f32 v150, v150, 0x3e0293ee, v252
	v_fmamk_f32 v151, v151, 0x3e0293ee, v252
	v_fmamk_f32 v152, v152, 0x3e0293ee, v252
	v_fmamk_f32 v153, v153, 0x3e0293ee, v252
	v_exp_f32_e32 v146, v146
	v_exp_f32_e32 v147, v147
	v_add_f32_e32 v253, 0, v146
	v_add_f32_e32 v253, v147, v253
	v_exp_f32_e32 v148, v148
	v_exp_f32_e32 v149, v149
	v_add_f32_e32 v253, v148, v253
	v_add_f32_e32 v253, v149, v253
	v_exp_f32_e32 v150, v150
	v_exp_f32_e32 v151, v151
	v_add_f32_e32 v253, v150, v253
	v_add_f32_e32 v253, v151, v253
	v_exp_f32_e32 v152, v152
	v_exp_f32_e32 v153, v153
	v_add_f32_e32 v253, v152, v253
	s_nop 0
	v_add_f32_e32 v253, v153, v253
	v_cvt_pk_bf16_f32 v153, v152, v153
	v_cvt_pk_bf16_f32 v152, v150, v151
	v_cvt_pk_bf16_f32 v151, v148, v149
	v_cvt_pk_bf16_f32 v150, v146, v147
	v_fmamk_f32 v154, v154, 0x3e0293ee, v252
	v_fmamk_f32 v155, v155, 0x3e0293ee, v252
	v_fmamk_f32 v156, v156, 0x3e0293ee, v252
	v_fmamk_f32 v157, v157, 0x3e0293ee, v252
	s_nop 1
	v_permlane32_swap_b32_e32 v150, v152
	v_permlane32_swap_b32_e32 v151, v153
	v_fmamk_f32 v158, v158, 0x3e0293ee, v252
	v_fmamk_f32 v159, v159, 0x3e0293ee, v252
	v_fmamk_f32 v160, v160, 0x3e0293ee, v252
	v_fmamk_f32 v161, v161, 0x3e0293ee, v252
	ds_read_b64_tr_b16 v[206:207], v224 offset:0x600
	ds_read_b64_tr_b16 v[208:209], v224 offset:0xe00
	s_waitcnt lgkmcnt(6)
	v_mfma_f32_32x32x16_bf16 v[2:17], v[150:153], v[194:197], v[2:17]
	v_exp_f32_e32 v154, v154
	v_exp_f32_e32 v155, v155
	ds_read_b64_tr_b16 v[194:195], v234 offset:0
	ds_read_b64_tr_b16 v[196:197], v234 offset:0x800
	s_waitcnt lgkmcnt(6)
	v_mfma_f32_32x32x16_bf16 v[114:129], v[150:153], v[198:201], v[114:129]
	v_add_f32_e32 v253, v154, v253
	v_add_f32_e32 v253, v155, v253
	v_exp_f32_e32 v156, v156
	ds_read_b64_tr_b16 v[198:199], v234 offset:0x200
	ds_read_b64_tr_b16 v[200:201], v234 offset:0xa00
	s_waitcnt lgkmcnt(6)
	v_mfma_f32_32x32x16_bf16 v[98:113], v[150:153], v[202:205], v[98:113]
	v_exp_f32_e32 v157, v157
	v_add_f32_e32 v253, v156, v253
	v_add_f32_e32 v253, v157, v253
	ds_read_b64_tr_b16 v[202:203], v234 offset:0x400
	ds_read_b64_tr_b16 v[204:205], v234 offset:0xc00
	s_waitcnt lgkmcnt(6)
	v_mfma_f32_32x32x16_bf16 v[82:97], v[150:153], v[206:209], v[82:97]
	v_exp_f32_e32 v158, v158
	v_exp_f32_e32 v159, v159
	ds_read_b64_tr_b16 v[206:207], v234 offset:0x600
	ds_read_b64_tr_b16 v[208:209], v234 offset:0xe00
	s_waitcnt lgkmcnt(6)
	v_mfma_f32_32x32x16_bf16 v[66:81], v[150:153], v[194:197], v[66:81]
	v_add_f32_e32 v253, v158, v253
	v_add_f32_e32 v253, v159, v253
	v_exp_f32_e32 v160, v160
	ds_read_b64_tr_b16 v[194:195], v224 offset:0x1000
	ds_read_b64_tr_b16 v[196:197], v224 offset:0x1800
	s_waitcnt lgkmcnt(6)
	v_mfma_f32_32x32x16_bf16 v[50:65], v[150:153], v[198:201], v[50:65]
	v_exp_f32_e32 v161, v161
	v_add_f32_e32 v253, v160, v253
	v_add_f32_e32 v253, v161, v253
	ds_read_b64_tr_b16 v[198:199], v224 offset:0x1200
	ds_read_b64_tr_b16 v[200:201], v224 offset:0x1a00
	s_waitcnt lgkmcnt(6)
	v_mfma_f32_32x32x16_bf16 v[34:49], v[150:153], v[202:205], v[34:49]
	v_cvt_pk_bf16_f32 v161, v160, v161
	v_cvt_pk_bf16_f32 v160, v158, v159
	v_cvt_pk_bf16_f32 v159, v156, v157
	v_cvt_pk_bf16_f32 v158, v154, v155
	v_fmamk_f32 v130, v130, 0x3e0293ee, v252
	v_fmamk_f32 v131, v131, 0x3e0293ee, v252
	v_fmamk_f32 v132, v132, 0x3e0293ee, v252
	v_fmamk_f32 v133, v133, 0x3e0293ee, v252
	ds_read_b64_tr_b16 v[202:203], v224 offset:0x1400
	ds_read_b64_tr_b16 v[204:205], v224 offset:0x1c00
	s_waitcnt lgkmcnt(6)
	v_mfma_f32_32x32x16_bf16 v[18:33], v[150:153], v[206:209], v[18:33]
	s_nop 1
	v_permlane32_swap_b32_e32 v158, v160
	v_permlane32_swap_b32_e32 v159, v161
	v_fmamk_f32 v134, v134, 0x3e0293ee, v252
	v_fmamk_f32 v135, v135, 0x3e0293ee, v252
	v_fmamk_f32 v136, v136, 0x3e0293ee, v252
	v_fmamk_f32 v137, v137, 0x3e0293ee, v252
	ds_read_b64_tr_b16 v[206:207], v224 offset:0x1600
	ds_read_b64_tr_b16 v[208:209], v224 offset:0x1e00
	s_waitcnt lgkmcnt(6)
	v_mfma_f32_32x32x16_bf16 v[2:17], v[158:161], v[194:197], v[2:17]
	v_exp_f32_e32 v130, v130
	v_exp_f32_e32 v131, v131
	ds_read_b64_tr_b16 v[194:195], v234 offset:0x1000
	ds_read_b64_tr_b16 v[196:197], v234 offset:0x1800
	s_waitcnt lgkmcnt(6)
	v_mfma_f32_32x32x16_bf16 v[114:129], v[158:161], v[198:201], v[114:129]
	v_add_f32_e32 v253, v130, v253
	v_add_f32_e32 v253, v131, v253
	v_exp_f32_e32 v132, v132
	ds_read_b64_tr_b16 v[198:199], v234 offset:0x1200
	ds_read_b64_tr_b16 v[200:201], v234 offset:0x1a00
	s_waitcnt lgkmcnt(6)
	v_mfma_f32_32x32x16_bf16 v[98:113], v[158:161], v[202:205], v[98:113]
	v_exp_f32_e32 v133, v133
	v_add_f32_e32 v253, v132, v253
	v_add_f32_e32 v253, v133, v253
	ds_read_b64_tr_b16 v[202:203], v234 offset:0x1400
	ds_read_b64_tr_b16 v[204:205], v234 offset:0x1c00
	s_waitcnt lgkmcnt(6)
	v_mfma_f32_32x32x16_bf16 v[82:97], v[158:161], v[206:209], v[82:97]
	v_exp_f32_e32 v134, v134
	v_exp_f32_e32 v135, v135
	ds_read_b64_tr_b16 v[206:207], v234 offset:0x1600
	ds_read_b64_tr_b16 v[208:209], v234 offset:0x1e00
	s_waitcnt lgkmcnt(6)
	v_mfma_f32_32x32x16_bf16 v[66:81], v[158:161], v[194:197], v[66:81]
	v_add_f32_e32 v253, v134, v253
	v_add_f32_e32 v253, v135, v253
	v_exp_f32_e32 v136, v136
	ds_read_b64_tr_b16 v[194:195], v224 offset:0x2000
	ds_read_b64_tr_b16 v[196:197], v224 offset:0x2800
	s_waitcnt lgkmcnt(6)
	v_mfma_f32_32x32x16_bf16 v[50:65], v[158:161], v[198:201], v[50:65]
	v_exp_f32_e32 v137, v137
	v_add_f32_e32 v253, v136, v253
	v_add_f32_e32 v253, v137, v253
	ds_read_b64_tr_b16 v[198:199], v224 offset:0x2200
	ds_read_b64_tr_b16 v[200:201], v224 offset:0x2a00
	s_waitcnt lgkmcnt(6)
	v_mfma_f32_32x32x16_bf16 v[34:49], v[158:161], v[202:205], v[34:49]
	v_cvt_pk_bf16_f32 v137, v136, v137
	v_cvt_pk_bf16_f32 v136, v134, v135
	v_cvt_pk_bf16_f32 v135, v132, v133
	v_cvt_pk_bf16_f32 v134, v130, v131
	v_fmamk_f32 v138, v138, 0x3e0293ee, v252
	v_fmamk_f32 v139, v139, 0x3e0293ee, v252
	v_fmamk_f32 v140, v140, 0x3e0293ee, v252
	v_fmamk_f32 v141, v141, 0x3e0293ee, v252
	ds_read_b64_tr_b16 v[202:203], v224 offset:0x2400
	ds_read_b64_tr_b16 v[204:205], v224 offset:0x2c00
	s_waitcnt lgkmcnt(6)
	v_mfma_f32_32x32x16_bf16 v[18:33], v[158:161], v[206:209], v[18:33]
	s_nop 1
	v_permlane32_swap_b32_e32 v134, v136
	v_permlane32_swap_b32_e32 v135, v137
	v_fmamk_f32 v142, v142, 0x3e0293ee, v252
	v_fmamk_f32 v143, v143, 0x3e0293ee, v252
	v_fmamk_f32 v144, v144, 0x3e0293ee, v252
	v_fmamk_f32 v145, v145, 0x3e0293ee, v252
	ds_read_b64_tr_b16 v[206:207], v224 offset:0x2600
	ds_read_b64_tr_b16 v[208:209], v224 offset:0x2e00
	s_waitcnt lgkmcnt(6)
	v_mfma_f32_32x32x16_bf16 v[2:17], v[134:137], v[194:197], v[2:17]
	v_exp_f32_e32 v138, v138
	v_exp_f32_e32 v139, v139
	ds_read_b64_tr_b16 v[194:195], v234 offset:0x2000
	ds_read_b64_tr_b16 v[196:197], v234 offset:0x2800
	s_waitcnt lgkmcnt(6)
	v_mfma_f32_32x32x16_bf16 v[114:129], v[134:137], v[198:201], v[114:129]
	v_add_f32_e32 v253, v138, v253
	v_add_f32_e32 v253, v139, v253
	v_exp_f32_e32 v140, v140
	ds_read_b64_tr_b16 v[198:199], v234 offset:0x2200
	ds_read_b64_tr_b16 v[200:201], v234 offset:0x2a00
	s_waitcnt lgkmcnt(6)
	v_mfma_f32_32x32x16_bf16 v[98:113], v[134:137], v[202:205], v[98:113]
	v_exp_f32_e32 v141, v141
	v_add_f32_e32 v253, v140, v253
	v_add_f32_e32 v253, v141, v253
	ds_read_b64_tr_b16 v[202:203], v234 offset:0x2400
	ds_read_b64_tr_b16 v[204:205], v234 offset:0x2c00
	s_waitcnt lgkmcnt(6)
	v_mfma_f32_32x32x16_bf16 v[82:97], v[134:137], v[206:209], v[82:97]
	v_exp_f32_e32 v142, v142
	v_exp_f32_e32 v143, v143
	ds_read_b64_tr_b16 v[206:207], v234 offset:0x2600
	ds_read_b64_tr_b16 v[208:209], v234 offset:0x2e00
	s_waitcnt lgkmcnt(6)
	v_mfma_f32_32x32x16_bf16 v[66:81], v[134:137], v[194:197], v[66:81]
	v_add_f32_e32 v253, v142, v253
	v_add_f32_e32 v253, v143, v253
	v_exp_f32_e32 v144, v144
	ds_read_b64_tr_b16 v[194:195], v224 offset:0x3000
	ds_read_b64_tr_b16 v[196:197], v224 offset:0x3800
	s_waitcnt lgkmcnt(6)
	v_mfma_f32_32x32x16_bf16 v[50:65], v[134:137], v[198:201], v[50:65]
	v_exp_f32_e32 v145, v145
	v_add_f32_e32 v253, v144, v253
	v_add_f32_e32 v247, v145, v253
	ds_read_b64_tr_b16 v[198:199], v224 offset:0x3200
	ds_read_b64_tr_b16 v[200:201], v224 offset:0x3a00
	s_waitcnt lgkmcnt(6)
	v_mfma_f32_32x32x16_bf16 v[34:49], v[134:137], v[202:205], v[34:49]
	v_cvt_pk_bf16_f32 v145, v144, v145
	v_cvt_pk_bf16_f32 v144, v142, v143
	v_cvt_pk_bf16_f32 v143, v140, v141
	v_cvt_pk_bf16_f32 v142, v138, v139
	v_mov_b32_e32 v248, v247
	ds_read_b64_tr_b16 v[202:203], v224 offset:0x3400
	ds_read_b64_tr_b16 v[204:205], v224 offset:0x3c00
	s_waitcnt lgkmcnt(6)
	v_mfma_f32_32x32x16_bf16 v[18:33], v[134:137], v[206:209], v[18:33]
	s_nop 1
	v_permlane32_swap_b32_e32 v142, v144
	v_permlane32_swap_b32_e32 v143, v145
	s_nop 1
	v_permlane32_swap_b32_e32 v247, v248
	ds_read_b64_tr_b16 v[206:207], v224 offset:0x3600
	ds_read_b64_tr_b16 v[208:209], v224 offset:0x3e00
	s_waitcnt lgkmcnt(6)
	v_mfma_f32_32x32x16_bf16 v[2:17], v[142:145], v[194:197], v[2:17]
	ds_read_b64_tr_b16 v[194:195], v234 offset:0x3000
	ds_read_b64_tr_b16 v[196:197], v234 offset:0x3800
	s_waitcnt lgkmcnt(6)
	v_mfma_f32_32x32x16_bf16 v[114:129], v[142:145], v[198:201], v[114:129]
	ds_read_b64_tr_b16 v[198:199], v234 offset:0x3200
	ds_read_b64_tr_b16 v[200:201], v234 offset:0x3a00
	s_waitcnt lgkmcnt(6)
	v_mfma_f32_32x32x16_bf16 v[98:113], v[142:145], v[202:205], v[98:113]
	ds_read_b64_tr_b16 v[202:203], v234 offset:0x3400
	ds_read_b64_tr_b16 v[204:205], v234 offset:0x3c00
	s_waitcnt lgkmcnt(6)
	v_mfma_f32_32x32x16_bf16 v[82:97], v[142:145], v[206:209], v[82:97]
	ds_read_b64_tr_b16 v[206:207], v234 offset:0x3600
	ds_read_b64_tr_b16 v[208:209], v234 offset:0x3e00
	s_waitcnt lgkmcnt(6)
	v_mfma_f32_32x32x16_bf16 v[66:81], v[142:145], v[194:197], v[66:81]
	s_waitcnt lgkmcnt(4)
	v_mfma_f32_32x32x16_bf16 v[50:65], v[142:145], v[198:201], v[50:65]
	s_waitcnt lgkmcnt(2)
	v_mfma_f32_32x32x16_bf16 v[34:49], v[142:145], v[202:205], v[34:49]
	s_waitcnt lgkmcnt(0)
	v_mfma_f32_32x32x16_bf16 v[18:33], v[142:145], v[206:209], v[18:33]
	s_add_i32 s14, s97, -1
	v_lshl_add_u64 v[222:223], v[216:217], 0, s[44:45]
	v_lshl_add_u64 v[220:221], v[218:219], 0, s[44:45]
	s_mov_b64 s[70:71], 0xa0000
	s_waitcnt vmcnt(0)

.LBB0_579:
	v_cndmask_b32_e64 v249, v251, v249, s[6:7]
	v_mul_f32_e32 v252, 0xbe0293ee, v249
	ds_read_b64_tr_b16 v[194:195], v235 offset:0
	ds_read_b64_tr_b16 v[196:197], v235 offset:0x800
	ds_read_b64_tr_b16 v[198:199], v235 offset:0x200
	ds_read_b64_tr_b16 v[200:201], v235 offset:0xa00
	ds_read_b64_tr_b16 v[202:203], v235 offset:0x400
	ds_read_b64_tr_b16 v[204:205], v235 offset:0xc00
	v_fmamk_f32 v146, v146, 0x3e0293ee, v252
	v_fmamk_f32 v147, v147, 0x3e0293ee, v252
	v_fmamk_f32 v148, v148, 0x3e0293ee, v252
	v_fmamk_f32 v149, v149, 0x3e0293ee, v252
	v_fmamk_f32 v150, v150, 0x3e0293ee, v252
	v_fmamk_f32 v151, v151, 0x3e0293ee, v252
	v_fmamk_f32 v152, v152, 0x3e0293ee, v252
	v_fmamk_f32 v153, v153, 0x3e0293ee, v252
	v_exp_f32_e32 v146, v146
	v_exp_f32_e32 v147, v147
	v_add_f32_e32 v253, 0, v146
	v_add_f32_e32 v253, v147, v253
	v_exp_f32_e32 v148, v148
	v_exp_f32_e32 v149, v149
	v_add_f32_e32 v253, v148, v253
	v_add_f32_e32 v253, v149, v253
	v_exp_f32_e32 v150, v150
	v_exp_f32_e32 v151, v151
	v_add_f32_e32 v253, v150, v253
	v_add_f32_e32 v253, v151, v253
	v_exp_f32_e32 v152, v152
	v_exp_f32_e32 v153, v153
	v_add_f32_e32 v253, v152, v253
	s_nop 0
	v_add_f32_e32 v253, v153, v253
	v_cvt_pk_bf16_f32 v153, v152, v153
	v_cvt_pk_bf16_f32 v152, v150, v151
	v_cvt_pk_bf16_f32 v151, v148, v149
	v_cvt_pk_bf16_f32 v150, v146, v147
	v_fmamk_f32 v154, v154, 0x3e0293ee, v252
	v_fmamk_f32 v155, v155, 0x3e0293ee, v252
	v_fmamk_f32 v156, v156, 0x3e0293ee, v252
	v_fmamk_f32 v157, v157, 0x3e0293ee, v252
	s_nop 1
	v_permlane32_swap_b32_e32 v150, v152
	v_permlane32_swap_b32_e32 v151, v153
	v_fmamk_f32 v158, v158, 0x3e0293ee, v252
	v_fmamk_f32 v159, v159, 0x3e0293ee, v252
	v_fmamk_f32 v160, v160, 0x3e0293ee, v252
	v_fmamk_f32 v161, v161, 0x3e0293ee, v252
	ds_read_b64_tr_b16 v[206:207], v235 offset:0x600
	ds_read_b64_tr_b16 v[208:209], v235 offset:0xe00
	s_waitcnt lgkmcnt(6)
	v_mfma_f32_32x32x16_bf16 v[2:17], v[150:153], v[194:197], v[2:17]
	v_exp_f32_e32 v154, v154
	v_exp_f32_e32 v155, v155
	ds_read_b64_tr_b16 v[194:195], v236 offset:0
	ds_read_b64_tr_b16 v[196:197], v236 offset:0x800
	s_waitcnt lgkmcnt(6)
	v_mfma_f32_32x32x16_bf16 v[114:129], v[150:153], v[198:201], v[114:129]
	v_add_f32_e32 v253, v154, v253
	v_add_f32_e32 v253, v155, v253
	v_exp_f32_e32 v156, v156
	ds_read_b64_tr_b16 v[198:199], v236 offset:0x200
	ds_read_b64_tr_b16 v[200:201], v236 offset:0xa00
	s_waitcnt lgkmcnt(6)
	v_mfma_f32_32x32x16_bf16 v[98:113], v[150:153], v[202:205], v[98:113]
	v_exp_f32_e32 v157, v157
	v_add_f32_e32 v253, v156, v253
	v_add_f32_e32 v253, v157, v253
	ds_read_b64_tr_b16 v[202:203], v236 offset:0x400
	ds_read_b64_tr_b16 v[204:205], v236 offset:0xc00
	s_waitcnt lgkmcnt(6)
	v_mfma_f32_32x32x16_bf16 v[82:97], v[150:153], v[206:209], v[82:97]
	v_exp_f32_e32 v158, v158
	v_exp_f32_e32 v159, v159
	ds_read_b64_tr_b16 v[206:207], v236 offset:0x600
	ds_read_b64_tr_b16 v[208:209], v236 offset:0xe00
	s_waitcnt lgkmcnt(6)
	v_mfma_f32_32x32x16_bf16 v[66:81], v[150:153], v[194:197], v[66:81]
	v_add_f32_e32 v253, v158, v253
	v_add_f32_e32 v253, v159, v253
	v_exp_f32_e32 v160, v160
	ds_read_b64_tr_b16 v[194:195], v235 offset:0x1000
	ds_read_b64_tr_b16 v[196:197], v235 offset:0x1800
	s_waitcnt lgkmcnt(6)
	v_mfma_f32_32x32x16_bf16 v[50:65], v[150:153], v[198:201], v[50:65]
	v_exp_f32_e32 v161, v161
	v_add_f32_e32 v253, v160, v253
	v_add_f32_e32 v253, v161, v253
	ds_read_b64_tr_b16 v[198:199], v235 offset:0x1200
	ds_read_b64_tr_b16 v[200:201], v235 offset:0x1a00
	s_waitcnt lgkmcnt(6)
	v_mfma_f32_32x32x16_bf16 v[34:49], v[150:153], v[202:205], v[34:49]
	v_cvt_pk_bf16_f32 v161, v160, v161
	v_cvt_pk_bf16_f32 v160, v158, v159
	v_cvt_pk_bf16_f32 v159, v156, v157
	v_cvt_pk_bf16_f32 v158, v154, v155
	v_fmamk_f32 v130, v130, 0x3e0293ee, v252
	v_fmamk_f32 v131, v131, 0x3e0293ee, v252
	v_fmamk_f32 v132, v132, 0x3e0293ee, v252
	v_fmamk_f32 v133, v133, 0x3e0293ee, v252
	ds_read_b64_tr_b16 v[202:203], v235 offset:0x1400
	ds_read_b64_tr_b16 v[204:205], v235 offset:0x1c00
	s_waitcnt lgkmcnt(6)
	v_mfma_f32_32x32x16_bf16 v[18:33], v[150:153], v[206:209], v[18:33]
	s_nop 1
	v_permlane32_swap_b32_e32 v158, v160
	v_permlane32_swap_b32_e32 v159, v161
	v_fmamk_f32 v134, v134, 0x3e0293ee, v252
	v_fmamk_f32 v135, v135, 0x3e0293ee, v252
	v_fmamk_f32 v136, v136, 0x3e0293ee, v252
	v_fmamk_f32 v137, v137, 0x3e0293ee, v252
	ds_read_b64_tr_b16 v[206:207], v235 offset:0x1600
	ds_read_b64_tr_b16 v[208:209], v235 offset:0x1e00
	s_waitcnt lgkmcnt(6)
	v_mfma_f32_32x32x16_bf16 v[2:17], v[158:161], v[194:197], v[2:17]
	v_exp_f32_e32 v130, v130
	v_exp_f32_e32 v131, v131
	ds_read_b64_tr_b16 v[194:195], v236 offset:0x1000
	ds_read_b64_tr_b16 v[196:197], v236 offset:0x1800
	s_waitcnt lgkmcnt(6)
	v_mfma_f32_32x32x16_bf16 v[114:129], v[158:161], v[198:201], v[114:129]
	v_add_f32_e32 v253, v130, v253
	v_add_f32_e32 v253, v131, v253
	v_exp_f32_e32 v132, v132
	ds_read_b64_tr_b16 v[198:199], v236 offset:0x1200
	ds_read_b64_tr_b16 v[200:201], v236 offset:0x1a00
	s_waitcnt lgkmcnt(6)
	v_mfma_f32_32x32x16_bf16 v[98:113], v[158:161], v[202:205], v[98:113]
	v_exp_f32_e32 v133, v133
	v_add_f32_e32 v253, v132, v253
	v_add_f32_e32 v253, v133, v253
	ds_read_b64_tr_b16 v[202:203], v236 offset:0x1400
	ds_read_b64_tr_b16 v[204:205], v236 offset:0x1c00
	s_waitcnt lgkmcnt(6)
	v_mfma_f32_32x32x16_bf16 v[82:97], v[158:161], v[206:209], v[82:97]
	v_exp_f32_e32 v134, v134
	v_exp_f32_e32 v135, v135
	ds_read_b64_tr_b16 v[206:207], v236 offset:0x1600
	ds_read_b64_tr_b16 v[208:209], v236 offset:0x1e00
	s_waitcnt lgkmcnt(6)
	v_mfma_f32_32x32x16_bf16 v[66:81], v[158:161], v[194:197], v[66:81]
	v_add_f32_e32 v253, v134, v253
	v_add_f32_e32 v253, v135, v253
	v_exp_f32_e32 v136, v136
	ds_read_b64_tr_b16 v[194:195], v235 offset:0x2000
	ds_read_b64_tr_b16 v[196:197], v235 offset:0x2800
	s_waitcnt lgkmcnt(6)
	v_mfma_f32_32x32x16_bf16 v[50:65], v[158:161], v[198:201], v[50:65]
	v_exp_f32_e32 v137, v137
	v_add_f32_e32 v253, v136, v253
	v_add_f32_e32 v253, v137, v253
	ds_read_b64_tr_b16 v[198:199], v235 offset:0x2200
	ds_read_b64_tr_b16 v[200:201], v235 offset:0x2a00
	s_waitcnt lgkmcnt(6)
	v_mfma_f32_32x32x16_bf16 v[34:49], v[158:161], v[202:205], v[34:49]
	v_cvt_pk_bf16_f32 v137, v136, v137
	v_cvt_pk_bf16_f32 v136, v134, v135
	v_cvt_pk_bf16_f32 v135, v132, v133
	v_cvt_pk_bf16_f32 v134, v130, v131
	v_fmamk_f32 v138, v138, 0x3e0293ee, v252
	v_fmamk_f32 v139, v139, 0x3e0293ee, v252
	v_fmamk_f32 v140, v140, 0x3e0293ee, v252
	v_fmamk_f32 v141, v141, 0x3e0293ee, v252
	ds_read_b64_tr_b16 v[202:203], v235 offset:0x2400
	ds_read_b64_tr_b16 v[204:205], v235 offset:0x2c00
	s_waitcnt lgkmcnt(6)
	v_mfma_f32_32x32x16_bf16 v[18:33], v[158:161], v[206:209], v[18:33]
	s_nop 1
	v_permlane32_swap_b32_e32 v134, v136
	v_permlane32_swap_b32_e32 v135, v137
	v_fmamk_f32 v142, v142, 0x3e0293ee, v252
	v_fmamk_f32 v143, v143, 0x3e0293ee, v252
	v_fmamk_f32 v144, v144, 0x3e0293ee, v252
	v_fmamk_f32 v145, v145, 0x3e0293ee, v252
	ds_read_b64_tr_b16 v[206:207], v235 offset:0x2600
	ds_read_b64_tr_b16 v[208:209], v235 offset:0x2e00
	s_waitcnt lgkmcnt(6)
	v_mfma_f32_32x32x16_bf16 v[2:17], v[134:137], v[194:197], v[2:17]
	v_exp_f32_e32 v138, v138
	v_exp_f32_e32 v139, v139
	ds_read_b64_tr_b16 v[194:195], v236 offset:0x2000
	ds_read_b64_tr_b16 v[196:197], v236 offset:0x2800
	s_waitcnt lgkmcnt(6)
	v_mfma_f32_32x32x16_bf16 v[114:129], v[134:137], v[198:201], v[114:129]
	v_add_f32_e32 v253, v138, v253
	v_add_f32_e32 v253, v139, v253
	v_exp_f32_e32 v140, v140
	ds_read_b64_tr_b16 v[198:199], v236 offset:0x2200
	ds_read_b64_tr_b16 v[200:201], v236 offset:0x2a00
	s_waitcnt lgkmcnt(6)
	v_mfma_f32_32x32x16_bf16 v[98:113], v[134:137], v[202:205], v[98:113]
	v_exp_f32_e32 v141, v141
	v_add_f32_e32 v253, v140, v253
	v_add_f32_e32 v253, v141, v253
	ds_read_b64_tr_b16 v[202:203], v236 offset:0x2400
	ds_read_b64_tr_b16 v[204:205], v236 offset:0x2c00
	s_waitcnt lgkmcnt(6)
	v_mfma_f32_32x32x16_bf16 v[82:97], v[134:137], v[206:209], v[82:97]
	v_exp_f32_e32 v142, v142
	v_exp_f32_e32 v143, v143
	ds_read_b64_tr_b16 v[206:207], v236 offset:0x2600
	ds_read_b64_tr_b16 v[208:209], v236 offset:0x2e00
	s_waitcnt lgkmcnt(6)
	v_mfma_f32_32x32x16_bf16 v[66:81], v[134:137], v[194:197], v[66:81]
	v_add_f32_e32 v253, v142, v253
	v_add_f32_e32 v253, v143, v253
	v_exp_f32_e32 v144, v144
	ds_read_b64_tr_b16 v[194:195], v235 offset:0x3000
	ds_read_b64_tr_b16 v[196:197], v235 offset:0x3800
	s_waitcnt lgkmcnt(6)
	v_mfma_f32_32x32x16_bf16 v[50:65], v[134:137], v[198:201], v[50:65]
	v_exp_f32_e32 v145, v145
	v_add_f32_e32 v253, v144, v253
	v_add_f32_e32 v146, v145, v253
	ds_read_b64_tr_b16 v[198:199], v235 offset:0x3200
	ds_read_b64_tr_b16 v[200:201], v235 offset:0x3a00
	s_waitcnt lgkmcnt(6)
	v_mfma_f32_32x32x16_bf16 v[34:49], v[134:137], v[202:205], v[34:49]
	v_cvt_pk_bf16_f32 v145, v144, v145
	v_cvt_pk_bf16_f32 v144, v142, v143
	v_cvt_pk_bf16_f32 v143, v140, v141
	v_cvt_pk_bf16_f32 v142, v138, v139
	v_mov_b32_e32 v147, v146
	ds_read_b64_tr_b16 v[202:203], v235 offset:0x3400
	ds_read_b64_tr_b16 v[204:205], v235 offset:0x3c00
	s_waitcnt lgkmcnt(6)
	v_mfma_f32_32x32x16_bf16 v[18:33], v[134:137], v[206:209], v[18:33]
	s_nop 1
	v_permlane32_swap_b32_e32 v142, v144
	v_permlane32_swap_b32_e32 v143, v145
	s_nop 1
	v_permlane32_swap_b32_e32 v146, v147
	ds_read_b64_tr_b16 v[206:207], v235 offset:0x3600
	ds_read_b64_tr_b16 v[208:209], v235 offset:0x3e00
	s_waitcnt lgkmcnt(6)
	v_mfma_f32_32x32x16_bf16 v[2:17], v[142:145], v[194:197], v[2:17]
	ds_read_b64_tr_b16 v[194:195], v236 offset:0x3000
	ds_read_b64_tr_b16 v[196:197], v236 offset:0x3800
	s_waitcnt lgkmcnt(6)
	v_mfma_f32_32x32x16_bf16 v[114:129], v[142:145], v[198:201], v[114:129]
	ds_read_b64_tr_b16 v[198:199], v236 offset:0x3200
	ds_read_b64_tr_b16 v[200:201], v236 offset:0x3a00
	s_waitcnt lgkmcnt(6)
	v_mfma_f32_32x32x16_bf16 v[98:113], v[142:145], v[202:205], v[98:113]
	ds_read_b64_tr_b16 v[202:203], v236 offset:0x3400
	ds_read_b64_tr_b16 v[204:205], v236 offset:0x3c00
	s_waitcnt lgkmcnt(6)
	v_mfma_f32_32x32x16_bf16 v[82:97], v[142:145], v[206:209], v[82:97]
	ds_read_b64_tr_b16 v[206:207], v236 offset:0x3600
	ds_read_b64_tr_b16 v[208:209], v236 offset:0x3e00
	s_waitcnt lgkmcnt(6)
	v_mfma_f32_32x32x16_bf16 v[66:81], v[142:145], v[194:197], v[66:81]
	s_waitcnt lgkmcnt(4)
	v_mfma_f32_32x32x16_bf16 v[50:65], v[142:145], v[198:201], v[50:65]
	s_waitcnt lgkmcnt(2)
	v_mfma_f32_32x32x16_bf16 v[34:49], v[142:145], v[202:205], v[34:49]
	s_waitcnt lgkmcnt(0)
	v_mfma_f32_32x32x16_bf16 v[18:33], v[142:145], v[206:209], v[18:33]
	s_branch .LBB0_562

.LBB0_593:
	v_cndmask_b32_e64 v249, v220, v249, s[6:7]
	v_mul_f32_e32 v252, 0xbe0293ee, v249
	ds_read_b64_tr_b16 v[194:195], v224 offset:0
	ds_read_b64_tr_b16 v[196:197], v224 offset:0x800
	ds_read_b64_tr_b16 v[198:199], v224 offset:0x200
	ds_read_b64_tr_b16 v[200:201], v224 offset:0xa00
	ds_read_b64_tr_b16 v[202:203], v224 offset:0x400
	ds_read_b64_tr_b16 v[204:205], v224 offset:0xc00
	v_fmamk_f32 v146, v146, 0x3e0293ee, v252
	v_fmamk_f32 v147, v147, 0x3e0293ee, v252
	v_fmamk_f32 v148, v148, 0x3e0293ee, v252
	v_fmamk_f32 v149, v149, 0x3e0293ee, v252
	v_fmamk_f32 v150, v150, 0x3e0293ee, v252
	v_fmamk_f32 v151, v151, 0x3e0293ee, v252
	v_fmamk_f32 v152, v152, 0x3e0293ee, v252
	v_fmamk_f32 v153, v153, 0x3e0293ee, v252
	v_exp_f32_e32 v146, v146
	v_exp_f32_e32 v147, v147
	v_add_f32_e32 v253, 0, v146
	v_add_f32_e32 v253, v147, v253
	v_exp_f32_e32 v148, v148
	v_exp_f32_e32 v149, v149
	v_add_f32_e32 v253, v148, v253
	v_add_f32_e32 v253, v149, v253
	v_exp_f32_e32 v150, v150
	v_exp_f32_e32 v151, v151
	v_add_f32_e32 v253, v150, v253
	v_add_f32_e32 v253, v151, v253
	v_exp_f32_e32 v152, v152
	v_exp_f32_e32 v153, v153
	v_add_f32_e32 v253, v152, v253
	s_nop 0
	v_add_f32_e32 v253, v153, v253
	v_cvt_pk_bf16_f32 v153, v152, v153
	v_cvt_pk_bf16_f32 v152, v150, v151
	v_cvt_pk_bf16_f32 v151, v148, v149
	v_cvt_pk_bf16_f32 v150, v146, v147
	v_fmamk_f32 v154, v154, 0x3e0293ee, v252
	v_fmamk_f32 v155, v155, 0x3e0293ee, v252
	v_fmamk_f32 v156, v156, 0x3e0293ee, v252
	v_fmamk_f32 v157, v157, 0x3e0293ee, v252
	s_nop 1
	v_permlane32_swap_b32_e32 v150, v152
	v_permlane32_swap_b32_e32 v151, v153
	v_fmamk_f32 v158, v158, 0x3e0293ee, v252
	v_fmamk_f32 v159, v159, 0x3e0293ee, v252
	v_fmamk_f32 v160, v160, 0x3e0293ee, v252
	v_fmamk_f32 v161, v161, 0x3e0293ee, v252
	ds_read_b64_tr_b16 v[206:207], v224 offset:0x600
	ds_read_b64_tr_b16 v[208:209], v224 offset:0xe00
	s_waitcnt lgkmcnt(6)
	v_mfma_f32_32x32x16_bf16 v[2:17], v[150:153], v[194:197], v[2:17]
	v_exp_f32_e32 v154, v154
	v_exp_f32_e32 v155, v155
	ds_read_b64_tr_b16 v[194:195], v234 offset:0
	ds_read_b64_tr_b16 v[196:197], v234 offset:0x800
	s_waitcnt lgkmcnt(6)
	v_mfma_f32_32x32x16_bf16 v[18:33], v[150:153], v[198:201], v[18:33]
	v_add_f32_e32 v253, v154, v253
	v_add_f32_e32 v253, v155, v253
	v_exp_f32_e32 v156, v156
	ds_read_b64_tr_b16 v[198:199], v234 offset:0x200
	ds_read_b64_tr_b16 v[200:201], v234 offset:0xa00
	s_waitcnt lgkmcnt(6)
	v_mfma_f32_32x32x16_bf16 v[34:49], v[150:153], v[202:205], v[34:49]
	v_exp_f32_e32 v157, v157
	v_add_f32_e32 v253, v156, v253
	v_add_f32_e32 v253, v157, v253
	ds_read_b64_tr_b16 v[202:203], v234 offset:0x400
	ds_read_b64_tr_b16 v[204:205], v234 offset:0xc00
	s_waitcnt lgkmcnt(6)
	v_mfma_f32_32x32x16_bf16 v[50:65], v[150:153], v[206:209], v[50:65]
	v_exp_f32_e32 v158, v158
	v_exp_f32_e32 v159, v159
	ds_read_b64_tr_b16 v[206:207], v234 offset:0x600
	ds_read_b64_tr_b16 v[208:209], v234 offset:0xe00
	s_waitcnt lgkmcnt(6)
	v_mfma_f32_32x32x16_bf16 v[66:81], v[150:153], v[194:197], v[66:81]
	v_add_f32_e32 v253, v158, v253
	v_add_f32_e32 v253, v159, v253
	v_exp_f32_e32 v160, v160
	ds_read_b64_tr_b16 v[194:195], v224 offset:0x1000
	ds_read_b64_tr_b16 v[196:197], v224 offset:0x1800
	s_waitcnt lgkmcnt(6)
	v_mfma_f32_32x32x16_bf16 v[82:97], v[150:153], v[198:201], v[82:97]
	v_exp_f32_e32 v161, v161
	v_add_f32_e32 v253, v160, v253
	v_add_f32_e32 v253, v161, v253
	ds_read_b64_tr_b16 v[198:199], v224 offset:0x1200
	ds_read_b64_tr_b16 v[200:201], v224 offset:0x1a00
	s_waitcnt lgkmcnt(6)
	v_mfma_f32_32x32x16_bf16 v[98:113], v[150:153], v[202:205], v[98:113]
	v_cvt_pk_bf16_f32 v161, v160, v161
	v_cvt_pk_bf16_f32 v160, v158, v159
	v_cvt_pk_bf16_f32 v159, v156, v157
	v_cvt_pk_bf16_f32 v158, v154, v155
	v_fmamk_f32 v130, v130, 0x3e0293ee, v252
	v_fmamk_f32 v131, v131, 0x3e0293ee, v252
	v_fmamk_f32 v132, v132, 0x3e0293ee, v252
	v_fmamk_f32 v133, v133, 0x3e0293ee, v252
	ds_read_b64_tr_b16 v[202:203], v224 offset:0x1400
	ds_read_b64_tr_b16 v[204:205], v224 offset:0x1c00
	s_waitcnt lgkmcnt(6)
	v_mfma_f32_32x32x16_bf16 v[114:129], v[150:153], v[206:209], v[114:129]
	s_nop 1
	v_permlane32_swap_b32_e32 v158, v160
	v_permlane32_swap_b32_e32 v159, v161
	v_fmamk_f32 v134, v134, 0x3e0293ee, v252
	v_fmamk_f32 v135, v135, 0x3e0293ee, v252
	v_fmamk_f32 v136, v136, 0x3e0293ee, v252
	v_fmamk_f32 v137, v137, 0x3e0293ee, v252
	ds_read_b64_tr_b16 v[206:207], v224 offset:0x1600
	ds_read_b64_tr_b16 v[208:209], v224 offset:0x1e00
	s_waitcnt lgkmcnt(6)
	v_mfma_f32_32x32x16_bf16 v[2:17], v[158:161], v[194:197], v[2:17]
	v_exp_f32_e32 v130, v130
	v_exp_f32_e32 v131, v131
	ds_read_b64_tr_b16 v[194:195], v234 offset:0x1000
	ds_read_b64_tr_b16 v[196:197], v234 offset:0x1800
	s_waitcnt lgkmcnt(6)
	v_mfma_f32_32x32x16_bf16 v[18:33], v[158:161], v[198:201], v[18:33]
	v_add_f32_e32 v253, v130, v253
	v_add_f32_e32 v253, v131, v253
	v_exp_f32_e32 v132, v132
	ds_read_b64_tr_b16 v[198:199], v234 offset:0x1200
	ds_read_b64_tr_b16 v[200:201], v234 offset:0x1a00
	s_waitcnt lgkmcnt(6)
	v_mfma_f32_32x32x16_bf16 v[34:49], v[158:161], v[202:205], v[34:49]
	v_exp_f32_e32 v133, v133
	v_add_f32_e32 v253, v132, v253
	v_add_f32_e32 v253, v133, v253
	ds_read_b64_tr_b16 v[202:203], v234 offset:0x1400
	ds_read_b64_tr_b16 v[204:205], v234 offset:0x1c00
	s_waitcnt lgkmcnt(6)
	v_mfma_f32_32x32x16_bf16 v[50:65], v[158:161], v[206:209], v[50:65]
	v_exp_f32_e32 v134, v134
	v_exp_f32_e32 v135, v135
	ds_read_b64_tr_b16 v[206:207], v234 offset:0x1600
	ds_read_b64_tr_b16 v[208:209], v234 offset:0x1e00
	s_waitcnt lgkmcnt(6)
	v_mfma_f32_32x32x16_bf16 v[66:81], v[158:161], v[194:197], v[66:81]
	v_add_f32_e32 v253, v134, v253
	v_add_f32_e32 v253, v135, v253
	v_exp_f32_e32 v136, v136
	ds_read_b64_tr_b16 v[194:195], v224 offset:0x2000
	ds_read_b64_tr_b16 v[196:197], v224 offset:0x2800
	s_waitcnt lgkmcnt(6)
	v_mfma_f32_32x32x16_bf16 v[82:97], v[158:161], v[198:201], v[82:97]
	v_exp_f32_e32 v137, v137
	v_add_f32_e32 v253, v136, v253
	v_add_f32_e32 v253, v137, v253
	ds_read_b64_tr_b16 v[198:199], v224 offset:0x2200
	ds_read_b64_tr_b16 v[200:201], v224 offset:0x2a00
	s_waitcnt lgkmcnt(6)
	v_mfma_f32_32x32x16_bf16 v[98:113], v[158:161], v[202:205], v[98:113]
	v_cvt_pk_bf16_f32 v137, v136, v137
	v_cvt_pk_bf16_f32 v136, v134, v135
	v_cvt_pk_bf16_f32 v135, v132, v133
	v_cvt_pk_bf16_f32 v134, v130, v131
	v_fmamk_f32 v138, v138, 0x3e0293ee, v252
	v_fmamk_f32 v139, v139, 0x3e0293ee, v252
	v_fmamk_f32 v140, v140, 0x3e0293ee, v252
	v_fmamk_f32 v141, v141, 0x3e0293ee, v252
	ds_read_b64_tr_b16 v[202:203], v224 offset:0x2400
	ds_read_b64_tr_b16 v[204:205], v224 offset:0x2c00
	s_waitcnt lgkmcnt(6)
	v_mfma_f32_32x32x16_bf16 v[114:129], v[158:161], v[206:209], v[114:129]
	s_nop 1
	v_permlane32_swap_b32_e32 v134, v136
	v_permlane32_swap_b32_e32 v135, v137
	v_fmamk_f32 v142, v142, 0x3e0293ee, v252
	v_fmamk_f32 v143, v143, 0x3e0293ee, v252
	v_fmamk_f32 v144, v144, 0x3e0293ee, v252
	v_fmamk_f32 v145, v145, 0x3e0293ee, v252
	ds_read_b64_tr_b16 v[206:207], v224 offset:0x2600
	ds_read_b64_tr_b16 v[208:209], v224 offset:0x2e00
	s_waitcnt lgkmcnt(6)
	v_mfma_f32_32x32x16_bf16 v[2:17], v[134:137], v[194:197], v[2:17]
	v_exp_f32_e32 v138, v138
	v_exp_f32_e32 v139, v139
	ds_read_b64_tr_b16 v[194:195], v234 offset:0x2000
	ds_read_b64_tr_b16 v[196:197], v234 offset:0x2800
	s_waitcnt lgkmcnt(6)
	v_mfma_f32_32x32x16_bf16 v[18:33], v[134:137], v[198:201], v[18:33]
	v_add_f32_e32 v253, v138, v253
	v_add_f32_e32 v253, v139, v253
	v_exp_f32_e32 v140, v140
	ds_read_b64_tr_b16 v[198:199], v234 offset:0x2200
	ds_read_b64_tr_b16 v[200:201], v234 offset:0x2a00
	s_waitcnt lgkmcnt(6)
	v_mfma_f32_32x32x16_bf16 v[34:49], v[134:137], v[202:205], v[34:49]
	v_exp_f32_e32 v141, v141
	v_add_f32_e32 v253, v140, v253
	v_add_f32_e32 v253, v141, v253
	ds_read_b64_tr_b16 v[202:203], v234 offset:0x2400
	ds_read_b64_tr_b16 v[204:205], v234 offset:0x2c00
	s_waitcnt lgkmcnt(6)
	v_mfma_f32_32x32x16_bf16 v[50:65], v[134:137], v[206:209], v[50:65]
	v_exp_f32_e32 v142, v142
	v_exp_f32_e32 v143, v143
	ds_read_b64_tr_b16 v[206:207], v234 offset:0x2600
	ds_read_b64_tr_b16 v[208:209], v234 offset:0x2e00
	s_waitcnt lgkmcnt(6)
	v_mfma_f32_32x32x16_bf16 v[66:81], v[134:137], v[194:197], v[66:81]
	v_add_f32_e32 v253, v142, v253
	v_add_f32_e32 v253, v143, v253
	v_exp_f32_e32 v144, v144
	ds_read_b64_tr_b16 v[194:195], v224 offset:0x3000
	ds_read_b64_tr_b16 v[196:197], v224 offset:0x3800
	s_waitcnt lgkmcnt(6)
	v_mfma_f32_32x32x16_bf16 v[82:97], v[134:137], v[198:201], v[82:97]
	v_exp_f32_e32 v145, v145
	v_add_f32_e32 v253, v144, v253
	v_add_f32_e32 v247, v145, v253
	ds_read_b64_tr_b16 v[198:199], v224 offset:0x3200
	ds_read_b64_tr_b16 v[200:201], v224 offset:0x3a00
	s_waitcnt lgkmcnt(6)
	v_mfma_f32_32x32x16_bf16 v[98:113], v[134:137], v[202:205], v[98:113]
	v_cvt_pk_bf16_f32 v145, v144, v145
	v_cvt_pk_bf16_f32 v144, v142, v143
	v_cvt_pk_bf16_f32 v143, v140, v141
	v_cvt_pk_bf16_f32 v142, v138, v139
	v_mov_b32_e32 v248, v247
	ds_read_b64_tr_b16 v[202:203], v224 offset:0x3400
	ds_read_b64_tr_b16 v[204:205], v224 offset:0x3c00
	s_waitcnt lgkmcnt(6)
	v_mfma_f32_32x32x16_bf16 v[114:129], v[134:137], v[206:209], v[114:129]
	s_nop 1
	v_permlane32_swap_b32_e32 v142, v144
	v_permlane32_swap_b32_e32 v143, v145
	s_nop 1
	v_permlane32_swap_b32_e32 v247, v248
	ds_read_b64_tr_b16 v[206:207], v224 offset:0x3600
	ds_read_b64_tr_b16 v[208:209], v224 offset:0x3e00
	s_waitcnt lgkmcnt(6)
	v_mfma_f32_32x32x16_bf16 v[2:17], v[142:145], v[194:197], v[2:17]
	ds_read_b64_tr_b16 v[194:195], v234 offset:0x3000
	ds_read_b64_tr_b16 v[196:197], v234 offset:0x3800
	s_waitcnt lgkmcnt(6)
	v_mfma_f32_32x32x16_bf16 v[18:33], v[142:145], v[198:201], v[18:33]
	ds_read_b64_tr_b16 v[198:199], v234 offset:0x3200
	ds_read_b64_tr_b16 v[200:201], v234 offset:0x3a00
	s_waitcnt lgkmcnt(6)
	v_mfma_f32_32x32x16_bf16 v[34:49], v[142:145], v[202:205], v[34:49]
	ds_read_b64_tr_b16 v[202:203], v234 offset:0x3400
	ds_read_b64_tr_b16 v[204:205], v234 offset:0x3c00
	s_waitcnt lgkmcnt(6)
	v_mfma_f32_32x32x16_bf16 v[50:65], v[142:145], v[206:209], v[50:65]
	ds_read_b64_tr_b16 v[206:207], v234 offset:0x3600
	ds_read_b64_tr_b16 v[208:209], v234 offset:0x3e00
	s_waitcnt lgkmcnt(6)
	v_mfma_f32_32x32x16_bf16 v[66:81], v[142:145], v[194:197], v[66:81]
	s_waitcnt lgkmcnt(4)
	v_mfma_f32_32x32x16_bf16 v[82:97], v[142:145], v[198:201], v[82:97]
	s_waitcnt lgkmcnt(2)
	v_mfma_f32_32x32x16_bf16 v[98:113], v[142:145], v[202:205], v[98:113]
	s_waitcnt lgkmcnt(0)
	v_mfma_f32_32x32x16_bf16 v[114:129], v[142:145], v[206:209], v[114:129]
	s_add_i32 s2, s51, -1
	v_lshl_add_u64 v[222:223], v[216:217], 0, s[44:45]
	v_lshl_add_u64 v[220:221], v[218:219], 0, s[44:45]
	s_waitcnt vmcnt(0)

.LBB0_601:
	v_cndmask_b32_e64 v249, v251, v249, s[6:7]
	v_mul_f32_e32 v252, 0xbe0293ee, v249
	ds_read_b64_tr_b16 v[194:195], v235 offset:0
	ds_read_b64_tr_b16 v[196:197], v235 offset:0x800
	ds_read_b64_tr_b16 v[198:199], v235 offset:0x200
	ds_read_b64_tr_b16 v[200:201], v235 offset:0xa00
	ds_read_b64_tr_b16 v[202:203], v235 offset:0x400
	ds_read_b64_tr_b16 v[204:205], v235 offset:0xc00
	v_fmamk_f32 v146, v146, 0x3e0293ee, v252
	v_fmamk_f32 v147, v147, 0x3e0293ee, v252
	v_fmamk_f32 v148, v148, 0x3e0293ee, v252
	v_fmamk_f32 v149, v149, 0x3e0293ee, v252
	v_fmamk_f32 v150, v150, 0x3e0293ee, v252
	v_fmamk_f32 v151, v151, 0x3e0293ee, v252
	v_fmamk_f32 v152, v152, 0x3e0293ee, v252
	v_fmamk_f32 v153, v153, 0x3e0293ee, v252
	v_exp_f32_e32 v146, v146
	v_exp_f32_e32 v147, v147
	v_add_f32_e32 v253, 0, v146
	v_add_f32_e32 v253, v147, v253
	v_exp_f32_e32 v148, v148
	v_exp_f32_e32 v149, v149
	v_add_f32_e32 v253, v148, v253
	v_add_f32_e32 v253, v149, v253
	v_exp_f32_e32 v150, v150
	v_exp_f32_e32 v151, v151
	v_add_f32_e32 v253, v150, v253
	v_add_f32_e32 v253, v151, v253
	v_exp_f32_e32 v152, v152
	v_exp_f32_e32 v153, v153
	v_add_f32_e32 v253, v152, v253
	s_nop 0
	v_add_f32_e32 v253, v153, v253
	v_cvt_pk_bf16_f32 v153, v152, v153
	v_cvt_pk_bf16_f32 v152, v150, v151
	v_cvt_pk_bf16_f32 v151, v148, v149
	v_cvt_pk_bf16_f32 v150, v146, v147
	v_fmamk_f32 v154, v154, 0x3e0293ee, v252
	v_fmamk_f32 v155, v155, 0x3e0293ee, v252
	v_fmamk_f32 v156, v156, 0x3e0293ee, v252
	v_fmamk_f32 v157, v157, 0x3e0293ee, v252
	s_nop 1
	v_permlane32_swap_b32_e32 v150, v152
	v_permlane32_swap_b32_e32 v151, v153
	v_fmamk_f32 v158, v158, 0x3e0293ee, v252
	v_fmamk_f32 v159, v159, 0x3e0293ee, v252
	v_fmamk_f32 v160, v160, 0x3e0293ee, v252
	v_fmamk_f32 v161, v161, 0x3e0293ee, v252
	ds_read_b64_tr_b16 v[206:207], v235 offset:0x600
	ds_read_b64_tr_b16 v[208:209], v235 offset:0xe00
	s_waitcnt lgkmcnt(6)
	v_mfma_f32_32x32x16_bf16 v[2:17], v[150:153], v[194:197], v[2:17]
	v_exp_f32_e32 v154, v154
	v_exp_f32_e32 v155, v155
	ds_read_b64_tr_b16 v[194:195], v236 offset:0
	ds_read_b64_tr_b16 v[196:197], v236 offset:0x800
	s_waitcnt lgkmcnt(6)
	v_mfma_f32_32x32x16_bf16 v[18:33], v[150:153], v[198:201], v[18:33]
	v_add_f32_e32 v253, v154, v253
	v_add_f32_e32 v253, v155, v253
	v_exp_f32_e32 v156, v156
	ds_read_b64_tr_b16 v[198:199], v236 offset:0x200
	ds_read_b64_tr_b16 v[200:201], v236 offset:0xa00
	s_waitcnt lgkmcnt(6)
	v_mfma_f32_32x32x16_bf16 v[34:49], v[150:153], v[202:205], v[34:49]
	v_exp_f32_e32 v157, v157
	v_add_f32_e32 v253, v156, v253
	v_add_f32_e32 v253, v157, v253
	ds_read_b64_tr_b16 v[202:203], v236 offset:0x400
	ds_read_b64_tr_b16 v[204:205], v236 offset:0xc00
	s_waitcnt lgkmcnt(6)
	v_mfma_f32_32x32x16_bf16 v[50:65], v[150:153], v[206:209], v[50:65]
	v_exp_f32_e32 v158, v158
	v_exp_f32_e32 v159, v159
	ds_read_b64_tr_b16 v[206:207], v236 offset:0x600
	ds_read_b64_tr_b16 v[208:209], v236 offset:0xe00
	s_waitcnt lgkmcnt(6)
	v_mfma_f32_32x32x16_bf16 v[66:81], v[150:153], v[194:197], v[66:81]
	v_add_f32_e32 v253, v158, v253
	v_add_f32_e32 v253, v159, v253
	v_exp_f32_e32 v160, v160
	ds_read_b64_tr_b16 v[194:195], v235 offset:0x1000
	ds_read_b64_tr_b16 v[196:197], v235 offset:0x1800
	s_waitcnt lgkmcnt(6)
	v_mfma_f32_32x32x16_bf16 v[82:97], v[150:153], v[198:201], v[82:97]
	v_exp_f32_e32 v161, v161
	v_add_f32_e32 v253, v160, v253
	v_add_f32_e32 v253, v161, v253
	ds_read_b64_tr_b16 v[198:199], v235 offset:0x1200
	ds_read_b64_tr_b16 v[200:201], v235 offset:0x1a00
	s_waitcnt lgkmcnt(6)
	v_mfma_f32_32x32x16_bf16 v[98:113], v[150:153], v[202:205], v[98:113]
	v_cvt_pk_bf16_f32 v161, v160, v161
	v_cvt_pk_bf16_f32 v160, v158, v159
	v_cvt_pk_bf16_f32 v159, v156, v157
	v_cvt_pk_bf16_f32 v158, v154, v155
	v_fmamk_f32 v130, v130, 0x3e0293ee, v252
	v_fmamk_f32 v131, v131, 0x3e0293ee, v252
	v_fmamk_f32 v132, v132, 0x3e0293ee, v252
	v_fmamk_f32 v133, v133, 0x3e0293ee, v252
	ds_read_b64_tr_b16 v[202:203], v235 offset:0x1400
	ds_read_b64_tr_b16 v[204:205], v235 offset:0x1c00
	s_waitcnt lgkmcnt(6)
	v_mfma_f32_32x32x16_bf16 v[114:129], v[150:153], v[206:209], v[114:129]
	s_nop 1
	v_permlane32_swap_b32_e32 v158, v160
	v_permlane32_swap_b32_e32 v159, v161
	v_fmamk_f32 v134, v134, 0x3e0293ee, v252
	v_fmamk_f32 v135, v135, 0x3e0293ee, v252
	v_fmamk_f32 v136, v136, 0x3e0293ee, v252
	v_fmamk_f32 v137, v137, 0x3e0293ee, v252
	ds_read_b64_tr_b16 v[206:207], v235 offset:0x1600
	ds_read_b64_tr_b16 v[208:209], v235 offset:0x1e00
	s_waitcnt lgkmcnt(6)
	v_mfma_f32_32x32x16_bf16 v[2:17], v[158:161], v[194:197], v[2:17]
	v_exp_f32_e32 v130, v130
	v_exp_f32_e32 v131, v131
	ds_read_b64_tr_b16 v[194:195], v236 offset:0x1000
	ds_read_b64_tr_b16 v[196:197], v236 offset:0x1800
	s_waitcnt lgkmcnt(6)
	v_mfma_f32_32x32x16_bf16 v[18:33], v[158:161], v[198:201], v[18:33]
	v_add_f32_e32 v253, v130, v253
	v_add_f32_e32 v253, v131, v253
	v_exp_f32_e32 v132, v132
	ds_read_b64_tr_b16 v[198:199], v236 offset:0x1200
	ds_read_b64_tr_b16 v[200:201], v236 offset:0x1a00
	s_waitcnt lgkmcnt(6)
	v_mfma_f32_32x32x16_bf16 v[34:49], v[158:161], v[202:205], v[34:49]
	v_exp_f32_e32 v133, v133
	v_add_f32_e32 v253, v132, v253
	v_add_f32_e32 v253, v133, v253
	ds_read_b64_tr_b16 v[202:203], v236 offset:0x1400
	ds_read_b64_tr_b16 v[204:205], v236 offset:0x1c00
	s_waitcnt lgkmcnt(6)
	v_mfma_f32_32x32x16_bf16 v[50:65], v[158:161], v[206:209], v[50:65]
	v_exp_f32_e32 v134, v134
	v_exp_f32_e32 v135, v135
	ds_read_b64_tr_b16 v[206:207], v236 offset:0x1600
	ds_read_b64_tr_b16 v[208:209], v236 offset:0x1e00
	s_waitcnt lgkmcnt(6)
	v_mfma_f32_32x32x16_bf16 v[66:81], v[158:161], v[194:197], v[66:81]
	v_add_f32_e32 v253, v134, v253
	v_add_f32_e32 v253, v135, v253
	v_exp_f32_e32 v136, v136
	ds_read_b64_tr_b16 v[194:195], v235 offset:0x2000
	ds_read_b64_tr_b16 v[196:197], v235 offset:0x2800
	s_waitcnt lgkmcnt(6)
	v_mfma_f32_32x32x16_bf16 v[82:97], v[158:161], v[198:201], v[82:97]
	v_exp_f32_e32 v137, v137
	v_add_f32_e32 v253, v136, v253
	v_add_f32_e32 v253, v137, v253
	ds_read_b64_tr_b16 v[198:199], v235 offset:0x2200
	ds_read_b64_tr_b16 v[200:201], v235 offset:0x2a00
	s_waitcnt lgkmcnt(6)
	v_mfma_f32_32x32x16_bf16 v[98:113], v[158:161], v[202:205], v[98:113]
	v_cvt_pk_bf16_f32 v137, v136, v137
	v_cvt_pk_bf16_f32 v136, v134, v135
	v_cvt_pk_bf16_f32 v135, v132, v133
	v_cvt_pk_bf16_f32 v134, v130, v131
	v_fmamk_f32 v138, v138, 0x3e0293ee, v252
	v_fmamk_f32 v139, v139, 0x3e0293ee, v252
	v_fmamk_f32 v140, v140, 0x3e0293ee, v252
	v_fmamk_f32 v141, v141, 0x3e0293ee, v252
	ds_read_b64_tr_b16 v[202:203], v235 offset:0x2400
	ds_read_b64_tr_b16 v[204:205], v235 offset:0x2c00
	s_waitcnt lgkmcnt(6)
	v_mfma_f32_32x32x16_bf16 v[114:129], v[158:161], v[206:209], v[114:129]
	s_nop 1
	v_permlane32_swap_b32_e32 v134, v136
	v_permlane32_swap_b32_e32 v135, v137
	v_fmamk_f32 v142, v142, 0x3e0293ee, v252
	v_fmamk_f32 v143, v143, 0x3e0293ee, v252
	v_fmamk_f32 v144, v144, 0x3e0293ee, v252
	v_fmamk_f32 v145, v145, 0x3e0293ee, v252
	ds_read_b64_tr_b16 v[206:207], v235 offset:0x2600
	ds_read_b64_tr_b16 v[208:209], v235 offset:0x2e00
	s_waitcnt lgkmcnt(6)
	v_mfma_f32_32x32x16_bf16 v[2:17], v[134:137], v[194:197], v[2:17]
	v_exp_f32_e32 v138, v138
	v_exp_f32_e32 v139, v139
	ds_read_b64_tr_b16 v[194:195], v236 offset:0x2000
	ds_read_b64_tr_b16 v[196:197], v236 offset:0x2800
	s_waitcnt lgkmcnt(6)
	v_mfma_f32_32x32x16_bf16 v[18:33], v[134:137], v[198:201], v[18:33]
	v_add_f32_e32 v253, v138, v253
	v_add_f32_e32 v253, v139, v253
	v_exp_f32_e32 v140, v140
	ds_read_b64_tr_b16 v[198:199], v236 offset:0x2200
	ds_read_b64_tr_b16 v[200:201], v236 offset:0x2a00
	s_waitcnt lgkmcnt(6)
	v_mfma_f32_32x32x16_bf16 v[34:49], v[134:137], v[202:205], v[34:49]
	v_exp_f32_e32 v141, v141
	v_add_f32_e32 v253, v140, v253
	v_add_f32_e32 v253, v141, v253
	ds_read_b64_tr_b16 v[202:203], v236 offset:0x2400
	ds_read_b64_tr_b16 v[204:205], v236 offset:0x2c00
	s_waitcnt lgkmcnt(6)
	v_mfma_f32_32x32x16_bf16 v[50:65], v[134:137], v[206:209], v[50:65]
	v_exp_f32_e32 v142, v142
	v_exp_f32_e32 v143, v143
	ds_read_b64_tr_b16 v[206:207], v236 offset:0x2600
	ds_read_b64_tr_b16 v[208:209], v236 offset:0x2e00
	s_waitcnt lgkmcnt(6)
	v_mfma_f32_32x32x16_bf16 v[66:81], v[134:137], v[194:197], v[66:81]
	v_add_f32_e32 v253, v142, v253
	v_add_f32_e32 v253, v143, v253
	v_exp_f32_e32 v144, v144
	ds_read_b64_tr_b16 v[194:195], v235 offset:0x3000
	ds_read_b64_tr_b16 v[196:197], v235 offset:0x3800
	s_waitcnt lgkmcnt(6)
	v_mfma_f32_32x32x16_bf16 v[82:97], v[134:137], v[198:201], v[82:97]
	v_exp_f32_e32 v145, v145
	v_add_f32_e32 v253, v144, v253
	v_add_f32_e32 v146, v145, v253
	ds_read_b64_tr_b16 v[198:199], v235 offset:0x3200
	ds_read_b64_tr_b16 v[200:201], v235 offset:0x3a00
	s_waitcnt lgkmcnt(6)
	v_mfma_f32_32x32x16_bf16 v[98:113], v[134:137], v[202:205], v[98:113]
	v_cvt_pk_bf16_f32 v145, v144, v145
	v_cvt_pk_bf16_f32 v144, v142, v143
	v_cvt_pk_bf16_f32 v143, v140, v141
	v_cvt_pk_bf16_f32 v142, v138, v139
	v_mov_b32_e32 v147, v146
	ds_read_b64_tr_b16 v[202:203], v235 offset:0x3400
	ds_read_b64_tr_b16 v[204:205], v235 offset:0x3c00
	s_waitcnt lgkmcnt(6)
	v_mfma_f32_32x32x16_bf16 v[114:129], v[134:137], v[206:209], v[114:129]
	s_nop 1
	v_permlane32_swap_b32_e32 v142, v144
	v_permlane32_swap_b32_e32 v143, v145
	s_nop 1
	v_permlane32_swap_b32_e32 v146, v147
	ds_read_b64_tr_b16 v[206:207], v235 offset:0x3600
	ds_read_b64_tr_b16 v[208:209], v235 offset:0x3e00
	s_waitcnt lgkmcnt(6)
	v_mfma_f32_32x32x16_bf16 v[2:17], v[142:145], v[194:197], v[2:17]
	ds_read_b64_tr_b16 v[194:195], v236 offset:0x3000
	ds_read_b64_tr_b16 v[196:197], v236 offset:0x3800
	s_waitcnt lgkmcnt(6)
	v_mfma_f32_32x32x16_bf16 v[18:33], v[142:145], v[198:201], v[18:33]
	ds_read_b64_tr_b16 v[198:199], v236 offset:0x3200
	ds_read_b64_tr_b16 v[200:201], v236 offset:0x3a00
	s_waitcnt lgkmcnt(6)
	v_mfma_f32_32x32x16_bf16 v[34:49], v[142:145], v[202:205], v[34:49]
	ds_read_b64_tr_b16 v[202:203], v236 offset:0x3400
	ds_read_b64_tr_b16 v[204:205], v236 offset:0x3c00
	s_waitcnt lgkmcnt(6)
	v_mfma_f32_32x32x16_bf16 v[50:65], v[142:145], v[206:209], v[50:65]
	ds_read_b64_tr_b16 v[206:207], v236 offset:0x3600
	ds_read_b64_tr_b16 v[208:209], v236 offset:0x3e00
	s_waitcnt lgkmcnt(6)
	v_mfma_f32_32x32x16_bf16 v[66:81], v[142:145], v[194:197], v[66:81]
	s_waitcnt lgkmcnt(4)
	v_mfma_f32_32x32x16_bf16 v[82:97], v[142:145], v[198:201], v[82:97]
	s_waitcnt lgkmcnt(2)
	v_mfma_f32_32x32x16_bf16 v[98:113], v[142:145], v[202:205], v[98:113]
	s_waitcnt lgkmcnt(0)
	v_mfma_f32_32x32x16_bf16 v[114:129], v[142:145], v[206:209], v[114:129]
	s_mov_b64 s[80:81], 0xc0100
	s_mov_b64 s[82:83], 0xe0100
	s_branch .LBB0_584
